# loop-edge: last PV accumulator chain kept contiguous (3 trailing MFMAs moved before the per-tile wait+barrier) in the three unmasked attention loops
# baseline (speedup 1.0000x reference)
.LBB0_626:
	s_lshl_b32 s2, s9, 14
	s_add_i32 s2, s58, s2
	v_lshl_add_u64 v[2:3], s[60:61], 0, v[0:1]
	v_lshl_add_u64 v[2:3], v[2:3], 0, s[96:97]
	s_mov_b32 m0, s2
	v_mov_b32_e32 v15, v1
	global_load_lds_dwordx4 v[2:3], off
	v_lshl_add_u64 v[2:3], s[60:61], 0, v[14:15]
	v_lshl_add_u64 v[2:3], v[2:3], 0, s[96:97]
	s_add_i32 m0, s2, 0x2000
	s_cmp_lt_u32 s27, s59
	global_load_lds_dwordx4 v[2:3], off
	s_cselect_b64 vcc, -1, 0
	v_add_u32_e32 v2, 0x30000, v0
	v_add_u32_e32 v3, 0x30000, v14
	s_cmp_lg_u64 vcc, 0
	v_cndmask_b32_e32 v14, v14, v3, vcc
	v_cndmask_b32_e32 v0, v0, v2, vcc
	s_addc_u32 s27, s27, 0
	s_mul_i32 s2, s12, 0x6000
	v_add_u32_e32 v15, s2, v236
	v_add_u32_e32 v6, v15, v241
	ds_read_b128 v[2:5], v6
	ds_read_b128 v[6:9], v6 offset:12288
	v_exp_f32_e32 v12, v96
	s_waitcnt lgkmcnt(0)
	v_mfma_f32_32x32x16_bf16 v[112:127], v[2:5], v[144:147], 0
	v_mov_b32_e32 v2, v97
	v_exp_f32_e32 v96, v98
	v_exp_f32_e32 v97, v99
	v_exp_f32_e32 v13, v2
	v_mfma_f32_32x32x16_bf16 v[128:143], v[6:9], v[144:147], 0
	v_add_u32_e32 v2, v15, v242
	ds_read_b128 v[4:7], v2
	ds_read_b128 v[8:11], v2 offset:12288
	v_mov_b32_e32 v2, v100
	v_mov_b32_e32 v3, v101
	v_exp_f32_e32 v98, v2
	v_exp_f32_e32 v99, v3
	v_exp_f32_e32 v100, v102
	v_exp_f32_e32 v101, v103
	v_cvt_pk_bf16_f32 v2, v12, v13
	s_waitcnt lgkmcnt(0)
	v_mfma_f32_32x32x16_bf16 v[112:127], v[4:7], v[148:151], v[112:127]
	v_cvt_pk_bf16_f32 v3, v96, v97
	v_cvt_pk_bf16_f32 v4, v98, v99
	v_cvt_pk_bf16_f32 v5, v100, v101
	s_nop 0
	v_permlane32_swap_b32_e32 v2, v4
	v_permlane32_swap_b32_e32 v3, v5
	v_mfma_f32_32x32x16_bf16 v[128:143], v[8:11], v[148:151], v[128:143]
	v_add_u32_e32 v10, v15, v243
	ds_read_b128 v[6:9], v10
	v_add_f32_e64 v102, v214, v12
	v_add_f32_e64 v103, v215, v13
	ds_read_b128 v[10:13], v10 offset:12288
	v_exp_f32_e32 v104, v104
	v_exp_f32_e32 v105, v105
	s_waitcnt lgkmcnt(0)
	v_mfma_f32_32x32x16_bf16 v[112:127], v[6:9], v[152:155], v[112:127]
	v_add_f32_e64 v6, v96, v102
	v_add_f32_e64 v7, v97, v103
	v_exp_f32_e32 v102, v106
	v_exp_f32_e32 v103, v107
	v_pk_add_f32 v[6:7], v[98:99], v[6:7]
	s_nop 0
	v_pk_add_f32 v[6:7], v[100:101], v[6:7]
	s_nop 0
	v_pk_add_f32 v[100:101], v[104:105], v[6:7]
	v_mfma_f32_32x32x16_bf16 v[128:143], v[10:13], v[152:155], v[128:143]
	v_add_u32_e32 v6, v15, v244
	ds_read_b128 v[8:11], v6
	ds_read_b128 v[96:99], v6 offset:12288
	v_exp_f32_e32 v106, v108
	v_exp_f32_e32 v107, v109
	v_exp_f32_e32 v108, v110
	v_exp_f32_e32 v109, v111
	v_cvt_pk_bf16_f32 v6, v104, v105
	s_waitcnt lgkmcnt(0)
	v_mfma_f32_32x32x16_bf16 v[112:127], v[8:11], v[156:159], v[112:127]
	v_cvt_pk_bf16_f32 v7, v102, v103
	v_cvt_pk_bf16_f32 v8, v106, v107
	v_cvt_pk_bf16_f32 v9, v108, v109
	s_nop 0
	v_permlane32_swap_b32_e32 v6, v8
	v_permlane32_swap_b32_e32 v7, v9
	v_mfma_f32_32x32x16_bf16 v[128:143], v[96:99], v[156:159], v[128:143]
	v_add_u32_e32 v96, v15, v245
	ds_read_b128 v[10:13], v96
	ds_read_b128 v[96:99], v96 offset:12288
	v_exp_f32_e32 v104, v80
	s_waitcnt lgkmcnt(0)
	v_mfma_f32_32x32x16_bf16 v[112:127], v[10:13], v[160:163], v[112:127]
	v_exp_f32_e32 v105, v81
	v_exp_f32_e32 v110, v82
	v_exp_f32_e32 v111, v83
	v_mfma_f32_32x32x16_bf16 v[128:143], v[96:99], v[160:163], v[128:143]
	v_add_u32_e32 v80, v15, v246
	ds_read_b128 v[10:13], v80
	ds_read_b128 v[80:83], v80 offset:12288
	v_exp_f32_e32 v96, v84
	v_exp_f32_e32 v97, v85
	v_exp_f32_e32 v98, v86
	v_exp_f32_e32 v99, v87
	v_cvt_pk_bf16_f32 v192, v104, v105
	v_cvt_pk_bf16_f32 v193, v110, v111
	v_cvt_pk_bf16_f32 v194, v96, v97
	v_cvt_pk_bf16_f32 v195, v98, v99
	s_waitcnt lgkmcnt(0)
	v_mfma_f32_32x32x16_bf16 v[128:143], v[80:83], v[164:167], v[128:143]
	v_permlane32_swap_b32_e32 v192, v194
	v_permlane32_swap_b32_e32 v193, v195
	v_mfma_f32_32x32x16_bf16 v[112:127], v[10:13], v[164:167], v[112:127]
	v_add_u32_e32 v80, v15, v247
	ds_read_b128 v[10:13], v80
	ds_read_b128 v[80:83], v80 offset:12288
	s_waitcnt lgkmcnt(0)
	v_mfma_f32_32x32x16_bf16 v[112:127], v[10:13], v[168:171], v[112:127]
	v_exp_f32_e32 v10, v88
	v_exp_f32_e32 v11, v89
	v_exp_f32_e32 v12, v90
	v_exp_f32_e32 v13, v91
	v_mfma_f32_32x32x16_bf16 v[128:143], v[80:83], v[168:171], v[128:143]
	v_mov_b32_e32 v88, v92
	v_mov_b32_e32 v89, v93
	v_add_f32_e64 v92, v102, v100
	v_add_f32_e64 v93, v103, v101
	v_add_u32_e32 v84, v15, v248
	v_pk_add_f32 v[92:93], v[106:107], v[92:93]
	v_pk_add_f32 v[92:93], v[108:109], v[92:93]
	v_pk_add_f32 v[92:93], v[104:105], v[92:93]
	v_exp_f32_e32 v88, v88
	v_pk_add_f32 v[92:93], v[110:111], v[92:93]
	v_exp_f32_e32 v89, v89
	v_pk_add_f32 v[92:93], v[96:97], v[92:93]
	ds_read_b128 v[80:83], v84
	ds_read_b128 v[84:87], v84 offset:12288
	v_exp_f32_e32 v90, v94
	v_exp_f32_e32 v91, v95
	v_pk_add_f32 v[92:93], v[98:99], v[92:93]
	s_waitcnt lgkmcnt(0)
; #define SBAR() __builtin_amdgcn_sched_barrier(0)
; #define VSET(S, d0) do { constexpr int b_ = (d0) * 512; TRRD(S##l0, b_); TRRD(S##h0, b_ + 2048); TRRD(S##l1, b_ + 4096); TRRD(S##h1, b_ + 6144); \
;         TRRD(S##l2, b_ + 8192); TRRD(S##h2, b_ + 10240); TRRD(S##l3, b_ + 12288); TRRD(S##h3, b_ + 14336); } while (0)
; #define LWAIT(n) do { asm volatile("s_waitcnt lgkmcnt(" #n ")" ::: "memory"); SBAR(); } while (0)
; __device__ __forceinline__ void pv_tile(f32x16* o, unsigned vb, bf16x8 pa0, bf16x8 pa1, bf16x8 pa2, bf16x8 pa3) {
;     ...
;     s16x4 Al0, Al1, Al2, Al3, Ah0, Ah1, Ah2, Ah3, Bl0, Bl1, Bl2, Bl3, Bh0, Bh1, Bh2, Bh3;
;     VSET(A, 0);
;     VSET(B, 1); LWAIT(8); VMMA(A, 0); SBAR();
;     VSET(A, 2); LWAIT(8); VMMA(B, 1); SBAR();
;     VSET(B, 3); LWAIT(8); VMMA(A, 2); SBAR();
;     LWAIT(0); VMMA(B, 3);
	v_mfma_f32_32x32x16_bf16 v[128:143], v[84:87], v[172:175], v[128:143]
	v_add_f32_e64 v92, v10, v92
	v_add_f32_e64 v93, v11, v93
	v_cvt_pk_bf16_f32 v10, v10, v11
	v_add_f32_e64 v92, v12, v92
	v_add_f32_e64 v93, v13, v93
	v_cvt_pk_bf16_f32 v11, v12, v13
	v_pk_add_f32 v[92:93], v[88:89], v[92:93]
	v_cvt_pk_bf16_f32 v12, v88, v89
	v_pk_add_f32 v[214:215], v[90:91], v[92:93]
	v_cvt_pk_bf16_f32 v13, v90, v91
	v_permlane32_swap_b32_e32 v10, v12
	s_nop 0
	v_permlane32_swap_b32_e32 v11, v13
	v_mfma_f32_32x32x16_bf16 v[112:127], v[80:83], v[172:175], v[112:127]
	v_add_u32_e32 v92, v15, v249
	v_add_u32_e32 v93, v15, v250
	v_add_u32_e32 v94, v15, v251
	v_add_u32_e32 v95, v15, v252
	ds_read_b128 v[96:99], v92
	ds_read_b128 v[100:103], v93
	ds_read_b128 v[104:107], v94
	ds_read_b128 v[80:83], v92 offset:12288
	ds_read_b128 v[84:87], v93 offset:12288
	ds_read_b128 v[88:91], v94 offset:12288
	ds_read_b128 v[222:225], v95 offset:12288
	ds_read_b128 v[92:95], v95
	s_waitcnt lgkmcnt(7)
	v_mfma_f32_32x32x16_bf16 v[112:127], v[96:99], v[176:179], v[112:127]
	s_waitcnt lgkmcnt(6)
	v_mfma_f32_32x32x16_bf16 v[112:127], v[100:103], v[180:183], v[112:127]
	s_waitcnt lgkmcnt(5)
	v_mfma_f32_32x32x16_bf16 v[112:127], v[104:107], v[184:187], v[112:127]
	s_waitcnt lgkmcnt(0)
	v_mfma_f32_32x32x16_bf16 v[96:111], v[92:95], v[188:191], v[112:127]
	v_mfma_f32_32x32x16_bf16 v[128:143], v[80:83], v[176:179], v[128:143]
	v_mfma_f32_32x32x16_bf16 v[128:143], v[84:87], v[180:183], v[128:143]
	v_mfma_f32_32x32x16_bf16 v[128:143], v[88:91], v[184:187], v[128:143]
	v_mfma_f32_32x32x16_bf16 v[80:95], v[222:225], v[188:191], v[128:143]
	v_lshl_add_u32 v15, s7, 14, v237
	ds_read_b64_tr_b16 v[112:113], v15 offset:0
	ds_read_b64_tr_b16 v[114:115], v15 offset:0x800
	ds_read_b64_tr_b16 v[116:117], v15 offset:0x1000
	ds_read_b64_tr_b16 v[118:119], v15 offset:0x1800
	ds_read_b64_tr_b16 v[120:121], v15 offset:0x2000
	ds_read_b64_tr_b16 v[122:123], v15 offset:0x2800
	ds_read_b64_tr_b16 v[124:125], v15 offset:0x3000
	ds_read_b64_tr_b16 v[126:127], v15 offset:0x3800
	ds_read_b64_tr_b16 v[128:129], v15 offset:0x200
	ds_read_b64_tr_b16 v[130:131], v15 offset:0xa00
	ds_read_b64_tr_b16 v[132:133], v15 offset:0x1200
	ds_read_b64_tr_b16 v[134:135], v15 offset:0x1a00
	ds_read_b64_tr_b16 v[136:137], v15 offset:0x2200
	ds_read_b64_tr_b16 v[138:139], v15 offset:0x2a00
	ds_read_b64_tr_b16 v[140:141], v15 offset:0x3200
	ds_read_b64_tr_b16 v[142:143], v15 offset:0x3a00
	s_waitcnt lgkmcnt(8)
	s_nop 0
	v_mfma_f32_32x32x16_bf16 v[64:79], v[2:5], v[112:115], v[64:79]
	v_mfma_f32_32x32x16_bf16 v[64:79], v[6:9], v[116:119], v[64:79]
	v_mfma_f32_32x32x16_bf16 v[64:79], v[192:195], v[120:123], v[64:79]
	v_mfma_f32_32x32x16_bf16 v[64:79], v[10:13], v[124:127], v[64:79]
	ds_read_b64_tr_b16 v[112:113], v15 offset:0x400
	ds_read_b64_tr_b16 v[114:115], v15 offset:0xc00
	ds_read_b64_tr_b16 v[116:117], v15 offset:0x1400
	ds_read_b64_tr_b16 v[118:119], v15 offset:0x1c00
	ds_read_b64_tr_b16 v[120:121], v15 offset:0x2400
	ds_read_b64_tr_b16 v[122:123], v15 offset:0x2c00
	ds_read_b64_tr_b16 v[124:125], v15 offset:0x3400
	ds_read_b64_tr_b16 v[126:127], v15 offset:0x3c00
	s_waitcnt lgkmcnt(8)
	v_mfma_f32_32x32x16_bf16 v[48:63], v[2:5], v[128:131], v[48:63]
	v_mfma_f32_32x32x16_bf16 v[48:63], v[6:9], v[132:135], v[48:63]
	v_mfma_f32_32x32x16_bf16 v[48:63], v[192:195], v[136:139], v[48:63]
	v_mfma_f32_32x32x16_bf16 v[48:63], v[10:13], v[140:143], v[48:63]
	ds_read_b64_tr_b16 v[128:129], v15 offset:0x600
	ds_read_b64_tr_b16 v[130:131], v15 offset:0xe00
	ds_read_b64_tr_b16 v[132:133], v15 offset:0x1600
	ds_read_b64_tr_b16 v[134:135], v15 offset:0x1e00
	ds_read_b64_tr_b16 v[136:137], v15 offset:0x2600
	ds_read_b64_tr_b16 v[138:139], v15 offset:0x2e00
	ds_read_b64_tr_b16 v[140:141], v15 offset:0x3600
	ds_read_b64_tr_b16 v[142:143], v15 offset:0x3e00
	s_waitcnt lgkmcnt(8)
	v_mfma_f32_32x32x16_bf16 v[32:47], v[2:5], v[112:115], v[32:47]
	v_mfma_f32_32x32x16_bf16 v[32:47], v[6:9], v[116:119], v[32:47]
	v_mfma_f32_32x32x16_bf16 v[32:47], v[192:195], v[120:123], v[32:47]
	v_mfma_f32_32x32x16_bf16 v[32:47], v[10:13], v[124:127], v[32:47]
	s_waitcnt lgkmcnt(0)
	v_mfma_f32_32x32x16_bf16 v[16:31], v[2:5], v[128:131], v[16:31]
	v_mfma_f32_32x32x16_bf16 v[16:31], v[6:9], v[132:135], v[16:31]
	v_mfma_f32_32x32x16_bf16 v[16:31], v[192:195], v[136:139], v[16:31]
	v_mfma_f32_32x32x16_bf16 v[16:31], v[10:13], v[140:143], v[16:31]
	s_waitcnt vmcnt(5)
	s_barrier
	s_add_i32 s13, s13, -1
	s_cmp_eq_u32 s13, 0
	s_cbranch_scc1 .LBB0_629
	s_mov_b32 s2, s12
	s_mov_b32 s12, s9
	s_mov_b32 s9, s7
	s_branch .LBB0_624

.LBB0_821:
	s_mov_b32 s12, s14
	s_lshl_b32 s14, s2, 14
	s_mov_b32 s63, s70
	s_mov_b32 s70, s2
	s_add_i32 s2, s9, s14
	s_add_i32 m0, s2, 0xc000
	v_add_u32_e32 v0, 0x98000, v163
	global_load_lds_dwordx4 v165, s[60:61]
	s_add_i32 m0, s2, 0xe000
	s_cmp_lt_u32 s83, s57
	s_cselect_b64 s[18:19], -1, 0
	s_and_b64 s[34:35], s[18:19], exec
	s_cselect_b32 s2, 0x98000, 0
	s_cmp_lg_u64 s[18:19], 0
	global_load_lds_dwordx4 v164, s[60:61]
	v_add_u32_e32 v164, s2, v164
	v_add_u32_e32 v165, s2, v165
	s_addc_u32 s83, s83, 0
	s_lshl_b32 s2, s63, 14
	s_add_i32 s2, s9, s2
	s_mov_b32 m0, s2
	v_add_u32_e32 v98, 0x98000, v162
	global_load_lds_dwordx4 v163, s[76:77]
	s_add_i32 m0, s2, 0x2000
	s_cmp_lt_u32 s62, s57
	global_load_lds_dwordx4 v162, s[76:77]
	s_cselect_b64 vcc, -1, 0
	s_cmp_lg_u64 vcc, 0
	v_cndmask_b32_e32 v162, v162, v98, vcc
	v_cndmask_b32_e32 v163, v163, v0, vcc
	s_addc_u32 s62, s62, 0
	v_lshl_add_u32 v0, s12, 14, v160
	v_add_u32_e32 v102, v0, v166
	v_exp_f32_e32 v150, v82
	v_exp_f32_e32 v151, v83
	v_exp_f32_e32 v152, v84
	v_exp_f32_e32 v153, v85
	ds_read_b128 v[98:101], v102
	ds_read_b128 v[114:117], v102 offset:8192
	v_exp_f32_e32 v170, v86
	v_exp_f32_e32 v171, v87
	v_exp_f32_e32 v172, v88
	v_exp_f32_e32 v173, v89
	v_cvt_pk_bf16_f32 v146, v150, v151
	v_cvt_pk_bf16_f32 v147, v152, v153
	v_cvt_pk_bf16_f32 v148, v170, v171
	v_cvt_pk_bf16_f32 v149, v172, v173
	s_waitcnt lgkmcnt(0)
	v_mfma_f32_32x32x16_bf16 v[98:113], v[98:101], v[130:133], 0
	v_permlane32_swap_b32_e32 v146, v148
	v_permlane32_swap_b32_e32 v147, v149
	v_mfma_f32_32x32x16_bf16 v[114:129], v[114:117], v[130:133], 0
	v_add_u32_e32 v86, v0, v167
	v_mov_b32_e32 v174, v92
	v_mov_b32_e32 v175, v93
	ds_read_b128 v[82:85], v86
	ds_read_b128 v[86:89], v86 offset:8192
	v_exp_f32_e32 v90, v90
	v_exp_f32_e32 v91, v91
	v_pk_add_f32 v[92:93], v[156:157], v[150:151]
	v_exp_f32_e32 v156, v174
	v_exp_f32_e32 v157, v175
	v_exp_f32_e32 v174, v94
	v_exp_f32_e32 v175, v95
	v_exp_f32_e32 v176, v96
	v_exp_f32_e32 v177, v97
	v_pk_add_f32 v[92:93], v[152:153], v[92:93]
	v_cvt_pk_bf16_f32 v150, v90, v91
	v_pk_add_f32 v[92:93], v[170:171], v[92:93]
	v_cvt_pk_bf16_f32 v151, v156, v157
	v_pk_add_f32 v[92:93], v[172:173], v[92:93]
	v_cvt_pk_bf16_f32 v152, v174, v175
	v_pk_add_f32 v[92:93], v[90:91], v[92:93]
	v_cvt_pk_bf16_f32 v153, v176, v177
	s_waitcnt lgkmcnt(0)
	v_mfma_f32_32x32x16_bf16 v[114:129], v[86:89], v[134:137], v[114:129]
	v_permlane32_swap_b32_e32 v150, v152
	v_permlane32_swap_b32_e32 v151, v153
	v_mfma_f32_32x32x16_bf16 v[98:113], v[82:85], v[134:137], v[98:113]
	v_add_u32_e32 v86, v0, v168
	v_exp_f32_e32 v178, v66
	v_exp_f32_e32 v179, v67
	v_exp_f32_e32 v180, v68
	v_exp_f32_e32 v181, v69
	ds_read_b128 v[82:85], v86
	ds_read_b128 v[86:89], v86 offset:8192
	v_exp_f32_e32 v182, v70
	v_exp_f32_e32 v183, v71
	v_exp_f32_e32 v184, v72
	v_exp_f32_e32 v185, v73
	v_cvt_pk_bf16_f32 v170, v178, v179
	v_cvt_pk_bf16_f32 v171, v180, v181
	v_cvt_pk_bf16_f32 v172, v182, v183
	v_cvt_pk_bf16_f32 v173, v184, v185
	s_waitcnt lgkmcnt(0)
	v_mfma_f32_32x32x16_bf16 v[98:113], v[82:85], v[138:141], v[98:113]
	v_permlane32_swap_b32_e32 v170, v172
	v_permlane32_swap_b32_e32 v171, v173
	v_mfma_f32_32x32x16_bf16 v[114:129], v[86:89], v[138:141], v[114:129]
	v_add_u32_e32 v0, v0, v169
	v_add_f32_e64 v156, v156, v92
	v_add_f32_e64 v157, v157, v93
	ds_read_b128 v[232:235], v0
	ds_read_b128 v[236:239], v0 offset:8192
	v_mov_b32_e32 v193, v81
	v_pk_add_f32 v[248:249], v[174:175], v[156:157]
	v_exp_f32_e32 v240, v74
	v_pk_add_f32 v[248:249], v[176:177], v[248:249]
	v_exp_f32_e32 v241, v75
	v_pk_add_f32 v[248:249], v[178:179], v[248:249]
	s_waitcnt lgkmcnt(0)
; #define SBAR() __builtin_amdgcn_sched_barrier(0)
; #define VSET(S, d0) do { constexpr int b_ = (d0) * 512; TRRD(S##l0, b_); TRRD(S##h0, b_ + 2048); TRRD(S##l1, b_ + 4096); TRRD(S##h1, b_ + 6144); \
;         TRRD(S##l2, b_ + 8192); TRRD(S##h2, b_ + 10240); TRRD(S##l3, b_ + 12288); TRRD(S##h3, b_ + 14336); } while (0)
; #define LWAIT(n) do { asm volatile("s_waitcnt lgkmcnt(" #n ")" ::: "memory"); SBAR(); } while (0)
; __device__ __forceinline__ void pv_tile(f32x16* o, unsigned vb, bf16x8 pa0, bf16x8 pa1, bf16x8 pa2, bf16x8 pa3) {
;     ...
;     s16x4 Al0, Al1, Al2, Al3, Ah0, Ah1, Ah2, Ah3, Bl0, Bl1, Bl2, Bl3, Bh0, Bh1, Bh2, Bh3;
;     VSET(A, 0);
;     VSET(B, 1); LWAIT(8); VMMA(A, 0); SBAR();
;     VSET(A, 2); LWAIT(8); VMMA(B, 1); SBAR();
;     VSET(B, 3); LWAIT(8); VMMA(A, 2); SBAR();
;     LWAIT(0); VMMA(B, 3);
	v_mfma_f32_32x32x16_bf16 v[82:97], v[232:235], v[142:145], v[98:113]
	v_exp_f32_e32 v242, v76
	v_exp_f32_e32 v243, v77
	v_pk_add_f32 v[250:251], v[180:181], v[248:249]
	v_exp_f32_e32 v244, v78
	v_exp_f32_e32 v245, v79
	v_pk_add_f32 v[248:249], v[182:183], v[250:251]
	v_exp_f32_e32 v246, v80
	v_mfma_f32_32x32x16_bf16 v[66:81], v[236:239], v[142:145], v[114:129]
	v_exp_f32_e32 v247, v193
	v_pk_add_f32 v[248:249], v[184:185], v[248:249]
	v_cvt_pk_bf16_f32 v98, v240, v241
	v_pk_add_f32 v[250:251], v[240:241], v[248:249]
	v_cvt_pk_bf16_f32 v99, v242, v243
	v_pk_add_f32 v[250:251], v[242:243], v[250:251]
	v_cvt_pk_bf16_f32 v100, v244, v245
	v_pk_add_f32 v[250:251], v[244:245], v[250:251]
	v_cvt_pk_bf16_f32 v101, v246, v247
	v_pk_add_f32 v[156:157], v[246:247], v[250:251]
	v_permlane32_swap_b32_e32 v98, v100
	v_permlane32_swap_b32_e32 v99, v101
	v_add_u32_e32 v0, s14, v161
	ds_read_b64_tr_b16 v[102:103], v0 offset:0
	ds_read_b64_tr_b16 v[104:105], v0 offset:0x800
	ds_read_b64_tr_b16 v[106:107], v0 offset:0x1000
	ds_read_b64_tr_b16 v[108:109], v0 offset:0x1800
	ds_read_b64_tr_b16 v[110:111], v0 offset:0x2000
	ds_read_b64_tr_b16 v[112:113], v0 offset:0x2800
	ds_read_b64_tr_b16 v[114:115], v0 offset:0x3000
	ds_read_b64_tr_b16 v[116:117], v0 offset:0x3800
	ds_read_b64_tr_b16 v[118:119], v0 offset:0x200
	ds_read_b64_tr_b16 v[120:121], v0 offset:0xa00
	ds_read_b64_tr_b16 v[122:123], v0 offset:0x1200
	ds_read_b64_tr_b16 v[124:125], v0 offset:0x1a00
	ds_read_b64_tr_b16 v[126:127], v0 offset:0x2200
	ds_read_b64_tr_b16 v[128:129], v0 offset:0x2a00
	ds_read_b64_tr_b16 v[174:175], v0 offset:0x3200
	ds_read_b64_tr_b16 v[176:177], v0 offset:0x3a00
	s_waitcnt lgkmcnt(8)
	s_nop 0
	v_mfma_f32_32x32x16_bf16 v[50:65], v[146:149], v[102:105], v[50:65]
	v_mfma_f32_32x32x16_bf16 v[50:65], v[150:153], v[106:109], v[50:65]
	v_mfma_f32_32x32x16_bf16 v[50:65], v[170:173], v[110:113], v[50:65]
	v_mfma_f32_32x32x16_bf16 v[50:65], v[98:101], v[114:117], v[50:65]
	ds_read_b64_tr_b16 v[102:103], v0 offset:0x400
	ds_read_b64_tr_b16 v[104:105], v0 offset:0xc00
	ds_read_b64_tr_b16 v[106:107], v0 offset:0x1400
	ds_read_b64_tr_b16 v[108:109], v0 offset:0x1c00
	ds_read_b64_tr_b16 v[110:111], v0 offset:0x2400
	ds_read_b64_tr_b16 v[112:113], v0 offset:0x2c00
	ds_read_b64_tr_b16 v[114:115], v0 offset:0x3400
	ds_read_b64_tr_b16 v[116:117], v0 offset:0x3c00
	s_waitcnt lgkmcnt(8)
	v_mfma_f32_32x32x16_bf16 v[34:49], v[146:149], v[118:121], v[34:49]
	v_mfma_f32_32x32x16_bf16 v[34:49], v[150:153], v[122:125], v[34:49]
	v_mfma_f32_32x32x16_bf16 v[34:49], v[170:173], v[126:129], v[34:49]
	v_mfma_f32_32x32x16_bf16 v[34:49], v[98:101], v[174:177], v[34:49]
	ds_read_b64_tr_b16 v[118:119], v0 offset:0x600
	ds_read_b64_tr_b16 v[120:121], v0 offset:0xe00
	ds_read_b64_tr_b16 v[122:123], v0 offset:0x1600
	ds_read_b64_tr_b16 v[124:125], v0 offset:0x1e00
	ds_read_b64_tr_b16 v[126:127], v0 offset:0x2600
	ds_read_b64_tr_b16 v[128:129], v0 offset:0x2e00
	ds_read_b64_tr_b16 v[174:175], v0 offset:0x3600
	ds_read_b64_tr_b16 v[176:177], v0 offset:0x3e00
	s_waitcnt lgkmcnt(8)
	v_mfma_f32_32x32x16_bf16 v[18:33], v[146:149], v[102:105], v[18:33]
	v_mfma_f32_32x32x16_bf16 v[18:33], v[150:153], v[106:109], v[18:33]
	v_mfma_f32_32x32x16_bf16 v[18:33], v[170:173], v[110:113], v[18:33]
	v_mfma_f32_32x32x16_bf16 v[18:33], v[98:101], v[114:117], v[18:33]
	s_waitcnt lgkmcnt(0)
	v_mfma_f32_32x32x16_bf16 v[2:17], v[146:149], v[118:121], v[2:17]
	v_mfma_f32_32x32x16_bf16 v[2:17], v[150:153], v[122:125], v[2:17]
	v_mfma_f32_32x32x16_bf16 v[2:17], v[170:173], v[126:129], v[2:17]
	v_mfma_f32_32x32x16_bf16 v[2:17], v[98:101], v[174:177], v[2:17]
	s_waitcnt vmcnt(4)
	s_barrier
	s_add_i32 s13, s13, -1
	s_cmp_lg_u32 s13, 0
	s_mov_b32 s2, s12
	s_mov_b32 s14, s63
	s_cbranch_scc1 .LBB0_821
	s_branch .LBB0_823

.LBB0_969:
	s_cmp_lt_i32 s83, s7
	s_cselect_b64 s[18:19], -1, 0
	s_and_b64 s[34:35], s[18:19], exec
	s_cselect_b32 s2, 0x98000, 0
	s_cmp_lg_u64 s[18:19], 0
	v_add_u32_e32 v186, s2, v186
	v_add_u32_e32 v187, s2, v187
	s_addc_u32 s83, s83, 0
	v_lshl_add_u32 v181, s57, 14, v15
	v_lshl_add_u32 v213, s13, 8, v212
	v_add_u32_e32 v10, v181, v188
	ds_read_b128 v[2:5], v213
	ds_read_b128 v[6:9], v10
	ds_read_b128 v[10:13], v10 offset:8192
	s_waitcnt lgkmcnt(0)
	v_mfma_f32_32x32x16_bf16 v[112:127], v[6:9], v[144:147], 0
	v_sub_f32_e32 v2, v180, v2
	v_sub_f32_e32 v3, v180, v3
	v_sub_f32_e32 v4, v180, v4
	v_sub_f32_e32 v5, v180, v5
	v_fmac_f32_e32 v2, 0x3e0293ee, v96
	v_fmac_f32_e32 v3, 0x3e0293ee, v97
	v_fmac_f32_e32 v4, 0x3e0293ee, v98
	v_fmac_f32_e32 v5, 0x3e0293ee, v99
	v_exp_f32_e32 v214, v2
	v_exp_f32_e32 v215, v3
	v_exp_f32_e32 v222, v4
	v_exp_f32_e32 v223, v5
	v_mfma_f32_32x32x16_bf16 v[128:143], v[10:13], v[144:147], 0
	ds_read_b128 v[2:5], v213 offset:32
	v_add_u32_e32 v10, v181, v189
	ds_read_b128 v[6:9], v10
	ds_read_b128 v[10:13], v10 offset:8192
	s_waitcnt lgkmcnt(0)
	v_mfma_f32_32x32x16_bf16 v[128:143], v[10:13], v[148:151], v[128:143]
	v_sub_f32_e32 v2, v180, v2
	v_sub_f32_e32 v3, v180, v3
	v_sub_f32_e32 v4, v180, v4
	v_sub_f32_e32 v5, v180, v5
	v_fmac_f32_e32 v2, 0x3e0293ee, v100
	v_fmac_f32_e32 v3, 0x3e0293ee, v101
	v_fmac_f32_e32 v4, 0x3e0293ee, v102
	v_fmac_f32_e32 v5, 0x3e0293ee, v103
	v_exp_f32_e32 v100, v2
	v_exp_f32_e32 v101, v3
	v_exp_f32_e32 v102, v4
	v_exp_f32_e32 v103, v5
	v_cvt_pk_bf16_f32 v2, v214, v215
	v_cvt_pk_bf16_f32 v3, v222, v223
	v_cvt_pk_bf16_f32 v4, v100, v101
	v_cvt_pk_bf16_f32 v5, v102, v103
	s_nop 0
	v_permlane32_swap_b32_e32 v2, v4
	v_permlane32_swap_b32_e32 v3, v5
	v_mfma_f32_32x32x16_bf16 v[112:127], v[6:9], v[148:151], v[112:127]
	ds_read_b128 v[6:9], v213 offset:64
	v_add_u32_e32 v96, v181, v190
	ds_read_b128 v[10:13], v96
	ds_read_b128 v[96:99], v96 offset:8192
	s_waitcnt lgkmcnt(0)
	v_mfma_f32_32x32x16_bf16 v[112:127], v[10:13], v[152:155], v[112:127]
	v_sub_f32_e32 v6, v180, v6
	v_sub_f32_e32 v7, v180, v7
	v_fmac_f32_e32 v6, 0x3e0293ee, v104
	v_fmac_f32_e32 v7, 0x3e0293ee, v105
	v_sub_f32_e32 v8, v180, v8
	v_sub_f32_e32 v9, v180, v9
	v_fmac_f32_e32 v8, 0x3e0293ee, v106
	v_fmac_f32_e32 v9, 0x3e0293ee, v107
	v_exp_f32_e32 v104, v6
	v_exp_f32_e32 v105, v7
	v_pk_add_f32 v[6:7], v[182:183], v[214:215]
	v_exp_f32_e32 v182, v8
	v_pk_add_f32 v[6:7], v[222:223], v[6:7]
	v_exp_f32_e32 v183, v9
	v_pk_add_f32 v[6:7], v[6:7], v[100:101]
	v_mfma_f32_32x32x16_bf16 v[128:143], v[96:99], v[152:155], v[128:143]
	v_add_f32_e64 v6, v102, v6
	v_add_f32_e64 v7, v103, v7
	v_add_f32_e64 v106, v6, v104
	v_add_f32_e64 v107, v7, v105
	ds_read_b128 v[6:9], v213 offset:96
	v_add_u32_e32 v96, v181, v191
	ds_read_b128 v[10:13], v96
	ds_read_b128 v[96:99], v96 offset:8192
	s_waitcnt lgkmcnt(0)
	v_mfma_f32_32x32x16_bf16 v[128:143], v[96:99], v[156:159], v[128:143]
	v_sub_f32_e32 v6, v180, v6
	v_sub_f32_e32 v7, v180, v7
	v_sub_f32_e32 v8, v180, v8
	v_sub_f32_e32 v9, v180, v9
	v_fmac_f32_e32 v6, 0x3e0293ee, v108
	v_fmac_f32_e32 v7, 0x3e0293ee, v109
	v_fmac_f32_e32 v8, 0x3e0293ee, v110
	v_fmac_f32_e32 v9, 0x3e0293ee, v111
	v_exp_f32_e32 v108, v6
	v_exp_f32_e32 v109, v7
	v_exp_f32_e32 v110, v8
	v_exp_f32_e32 v111, v9
	v_cvt_pk_bf16_f32 v6, v104, v105
	v_cvt_pk_bf16_f32 v7, v182, v183
	v_cvt_pk_bf16_f32 v8, v108, v109
	v_cvt_pk_bf16_f32 v9, v110, v111
	s_nop 0
	v_permlane32_swap_b32_e32 v6, v8
	v_permlane32_swap_b32_e32 v7, v9
	v_mfma_f32_32x32x16_bf16 v[112:127], v[10:13], v[156:159], v[112:127]
	v_add_u32_e32 v100, v181, v192
	ds_read_b128 v[10:13], v213 offset:128
	ds_read_b128 v[96:99], v100
	ds_read_b128 v[100:103], v100 offset:8192
	s_waitcnt lgkmcnt(0)
	v_mfma_f32_32x32x16_bf16 v[112:127], v[96:99], v[160:163], v[112:127]
	v_sub_f32_e32 v10, v180, v10
	v_sub_f32_e32 v11, v180, v11
	v_fmac_f32_e32 v10, 0x3e0293ee, v80
	v_fmac_f32_e32 v11, 0x3e0293ee, v81
	v_exp_f32_e32 v104, v10
	v_exp_f32_e32 v105, v11
	v_sub_f32_e32 v12, v180, v12
	v_sub_f32_e32 v13, v180, v13
	v_fmac_f32_e32 v12, 0x3e0293ee, v82
	v_fmac_f32_e32 v13, 0x3e0293ee, v83
	v_exp_f32_e32 v214, v12
	v_exp_f32_e32 v215, v13
	v_mfma_f32_32x32x16_bf16 v[128:143], v[100:103], v[160:163], v[128:143]
	ds_read_b128 v[10:13], v213 offset:160
	v_add_u32_e32 v96, v181, v193
	ds_read_b128 v[80:83], v96
	ds_read_b128 v[96:99], v96 offset:8192
	s_waitcnt lgkmcnt(0)
	v_mfma_f32_32x32x16_bf16 v[128:143], v[96:99], v[164:167], v[128:143]
	v_sub_f32_e32 v10, v180, v10
	v_sub_f32_e32 v11, v180, v11
	v_sub_f32_e32 v12, v180, v12
	v_sub_f32_e32 v13, v180, v13
	v_fmac_f32_e32 v10, 0x3e0293ee, v84
	v_fmac_f32_e32 v11, 0x3e0293ee, v85
	v_fmac_f32_e32 v12, 0x3e0293ee, v86
	v_fmac_f32_e32 v13, 0x3e0293ee, v87
	v_exp_f32_e32 v100, v10
	v_exp_f32_e32 v101, v11
	v_exp_f32_e32 v102, v12
	v_exp_f32_e32 v103, v13
	v_cvt_pk_bf16_f32 v10, v104, v105
	v_cvt_pk_bf16_f32 v11, v214, v215
	v_cvt_pk_bf16_f32 v12, v100, v101
	v_cvt_pk_bf16_f32 v13, v102, v103
	s_nop 0
	v_permlane32_swap_b32_e32 v10, v12
	v_permlane32_swap_b32_e32 v11, v13
	v_mfma_f32_32x32x16_bf16 v[112:127], v[80:83], v[164:167], v[112:127]
	v_add_u32_e32 v96, v181, v194
	ds_read_b128 v[80:83], v213 offset:192
	ds_read_b128 v[84:87], v96
	ds_read_b128 v[96:99], v96 offset:8192
	s_waitcnt lgkmcnt(0)
; #define SBAR() __builtin_amdgcn_sched_barrier(0)
; #define VSET(S, d0) do { constexpr int b_ = (d0) * 512; TRRD(S##l0, b_); TRRD(S##h0, b_ + 2048); TRRD(S##l1, b_ + 4096); TRRD(S##h1, b_ + 6144); \
;         TRRD(S##l2, b_ + 8192); TRRD(S##h2, b_ + 10240); TRRD(S##l3, b_ + 12288); TRRD(S##h3, b_ + 14336); } while (0)
; #define LWAIT(n) do { asm volatile("s_waitcnt lgkmcnt(" #n ")" ::: "memory"); SBAR(); } while (0)
; __device__ __forceinline__ void pv_tile(f32x16* o, unsigned vb, bf16x8 pa0, bf16x8 pa1, bf16x8 pa2, bf16x8 pa3) {
;     ...
;     s16x4 Al0, Al1, Al2, Al3, Ah0, Ah1, Ah2, Ah3, Bl0, Bl1, Bl2, Bl3, Bh0, Bh1, Bh2, Bh3;
;     VSET(A, 0);
;     VSET(B, 1); LWAIT(8); VMMA(A, 0); SBAR();
;     VSET(A, 2); LWAIT(8); VMMA(B, 1); SBAR();
;     VSET(B, 3); LWAIT(8); VMMA(A, 2); SBAR();
;     LWAIT(0); VMMA(B, 3);
	v_mfma_f32_32x32x16_bf16 v[112:127], v[84:87], v[168:171], v[112:127]
	v_sub_f32_e32 v80, v180, v80
	v_sub_f32_e32 v81, v180, v81
	v_sub_f32_e32 v82, v180, v82
	v_sub_f32_e32 v83, v180, v83
	v_fmac_f32_e32 v80, 0x3e0293ee, v88
	v_fmac_f32_e32 v81, 0x3e0293ee, v89
	v_fmac_f32_e32 v82, 0x3e0293ee, v90
	v_fmac_f32_e32 v83, 0x3e0293ee, v91
	v_exp_f32_e32 v88, v80
	v_exp_f32_e32 v89, v81
	v_exp_f32_e32 v90, v82
	v_exp_f32_e32 v91, v83
	v_mfma_f32_32x32x16_bf16 v[128:143], v[96:99], v[168:171], v[128:143]
	ds_read_b128 v[80:83], v213 offset:224
	v_add_u32_e32 v96, v181, v195
	ds_read_b128 v[84:87], v96
	ds_read_b128 v[232:235], v96 offset:8192
	v_cvt_pk_bf16_f32 v236, v88, v89
	v_cvt_pk_bf16_f32 v237, v90, v91
	s_waitcnt lgkmcnt(0)
	v_sub_f32_e32 v80, v180, v80
	v_sub_f32_e32 v81, v180, v81
	v_fmac_f32_e32 v80, 0x3e0293ee, v92
	v_fmac_f32_e32 v81, 0x3e0293ee, v93
	v_pk_add_f32 v[92:93], v[182:183], v[106:107]
	v_sub_f32_e32 v82, v180, v82
	v_pk_add_f32 v[92:93], v[92:93], v[108:109]
	v_sub_f32_e32 v83, v180, v83
	v_pk_add_f32 v[92:93], v[110:111], v[92:93]
	v_fmac_f32_e32 v82, 0x3e0293ee, v94
	v_pk_add_f32 v[92:93], v[92:93], v[104:105]
	v_fmac_f32_e32 v83, 0x3e0293ee, v95
	v_pk_add_f32 v[92:93], v[214:215], v[92:93]
	v_exp_f32_e32 v80, v80
	v_exp_f32_e32 v81, v81
	v_pk_add_f32 v[92:93], v[92:93], v[100:101]
	v_exp_f32_e32 v82, v82
	v_exp_f32_e32 v83, v83
	v_pk_add_f32 v[92:93], v[102:103], v[92:93]
	v_pk_add_f32 v[92:93], v[92:93], v[88:89]
	v_pk_add_f32 v[92:93], v[90:91], v[92:93]
	v_pk_add_f32 v[92:93], v[92:93], v[80:81]
	v_pk_add_f32 v[182:183], v[82:83], v[92:93]
	v_cvt_pk_bf16_f32 v238, v80, v81
	v_mfma_f32_32x32x16_bf16 v[96:111], v[84:87], v[172:175], v[112:127]
	v_cvt_pk_bf16_f32 v239, v82, v83
	v_permlane32_swap_b32_e32 v236, v238
	v_mfma_f32_32x32x16_bf16 v[80:95], v[232:235], v[172:175], v[128:143]
	v_permlane32_swap_b32_e32 v237, v239
	v_add_u32_e32 v181, s15, v179
	ds_read_b64_tr_b16 v[112:113], v181 offset:0
	ds_read_b64_tr_b16 v[114:115], v181 offset:0x800
	ds_read_b64_tr_b16 v[116:117], v181 offset:0x1000
	ds_read_b64_tr_b16 v[118:119], v181 offset:0x1800
	ds_read_b64_tr_b16 v[120:121], v181 offset:0x2000
	ds_read_b64_tr_b16 v[122:123], v181 offset:0x2800
	ds_read_b64_tr_b16 v[124:125], v181 offset:0x3000
	ds_read_b64_tr_b16 v[126:127], v181 offset:0x3800
	ds_read_b64_tr_b16 v[128:129], v181 offset:0x200
	ds_read_b64_tr_b16 v[130:131], v181 offset:0xa00
	ds_read_b64_tr_b16 v[132:133], v181 offset:0x1200
	ds_read_b64_tr_b16 v[134:135], v181 offset:0x1a00
	ds_read_b64_tr_b16 v[136:137], v181 offset:0x2200
	ds_read_b64_tr_b16 v[138:139], v181 offset:0x2a00
	ds_read_b64_tr_b16 v[140:141], v181 offset:0x3200
	ds_read_b64_tr_b16 v[142:143], v181 offset:0x3a00
	s_waitcnt lgkmcnt(8)
	s_nop 0
	v_mfma_f32_32x32x16_bf16 v[64:79], v[2:5], v[112:115], v[64:79]
	v_mfma_f32_32x32x16_bf16 v[64:79], v[6:9], v[116:119], v[64:79]
	v_mfma_f32_32x32x16_bf16 v[64:79], v[10:13], v[120:123], v[64:79]
	v_mfma_f32_32x32x16_bf16 v[64:79], v[236:239], v[124:127], v[64:79]
	ds_read_b64_tr_b16 v[112:113], v181 offset:0x400
	ds_read_b64_tr_b16 v[114:115], v181 offset:0xc00
	ds_read_b64_tr_b16 v[116:117], v181 offset:0x1400
	ds_read_b64_tr_b16 v[118:119], v181 offset:0x1c00
	ds_read_b64_tr_b16 v[120:121], v181 offset:0x2400
	ds_read_b64_tr_b16 v[122:123], v181 offset:0x2c00
	ds_read_b64_tr_b16 v[124:125], v181 offset:0x3400
	ds_read_b64_tr_b16 v[126:127], v181 offset:0x3c00
	s_waitcnt lgkmcnt(8)
	v_mfma_f32_32x32x16_bf16 v[48:63], v[2:5], v[128:131], v[48:63]
	v_mfma_f32_32x32x16_bf16 v[48:63], v[6:9], v[132:135], v[48:63]
	v_mfma_f32_32x32x16_bf16 v[48:63], v[10:13], v[136:139], v[48:63]
	v_mfma_f32_32x32x16_bf16 v[48:63], v[236:239], v[140:143], v[48:63]
	ds_read_b64_tr_b16 v[128:129], v181 offset:0x600
	ds_read_b64_tr_b16 v[130:131], v181 offset:0xe00
	ds_read_b64_tr_b16 v[132:133], v181 offset:0x1600
	ds_read_b64_tr_b16 v[134:135], v181 offset:0x1e00
	ds_read_b64_tr_b16 v[136:137], v181 offset:0x2600
	ds_read_b64_tr_b16 v[138:139], v181 offset:0x2e00
	ds_read_b64_tr_b16 v[140:141], v181 offset:0x3600
	ds_read_b64_tr_b16 v[142:143], v181 offset:0x3e00
	s_waitcnt lgkmcnt(8)
	v_mfma_f32_32x32x16_bf16 v[32:47], v[2:5], v[112:115], v[32:47]
	v_mfma_f32_32x32x16_bf16 v[32:47], v[6:9], v[116:119], v[32:47]
	v_mfma_f32_32x32x16_bf16 v[32:47], v[10:13], v[120:123], v[32:47]
	v_mfma_f32_32x32x16_bf16 v[32:47], v[236:239], v[124:127], v[32:47]
	s_waitcnt lgkmcnt(0)
	v_mfma_f32_32x32x16_bf16 v[16:31], v[2:5], v[128:131], v[16:31]
	v_mfma_f32_32x32x16_bf16 v[16:31], v[6:9], v[132:135], v[16:31]
	v_mfma_f32_32x32x16_bf16 v[16:31], v[10:13], v[136:139], v[16:31]
	v_mfma_f32_32x32x16_bf16 v[16:31], v[236:239], v[140:143], v[16:31]
	s_waitcnt vmcnt(5)
	s_barrier
	s_add_i32 s6, s6, 1
	s_cmp_ge_i32 s6, s8
	s_mov_b32 s15, s57
	s_mov_b32 s57, s63
	s_mov_b32 s63, s13
	s_cbranch_scc1 .LBB0_973
